# P14->P15 split-phase barrier: XCD-local panel sync for merged at P15 start, global arrival (with XCD-leader writeback) checked in the P15 K loop before the output stores
# speedup vs baseline: 1.0326x; 1.0035x over previous
.LBB0_1781:
	s_waitcnt vmcnt(0)
	s_waitcnt vmcnt(0) lgkmcnt(0)
	s_barrier
	s_and_saveexec_b64 s[8:9], s[92:93]
	s_cbranch_execz .LBB0_1833
	s_and_b32 s0, s2, 7
	s_lshl_b32 s0, s0, 3
	s_lshr_b32 s1, s2, 5
	s_add_i32 s1, s0, s1
	s_lshl_b32 s1, s1, 8
	s_add_i32 s1, s1, 0x2b5d028
	v_mov_b32_e32 v2, s1
	v_mov_b32_e32 v3, 1
	global_atomic_add v2, v3, s[88:89]
	v_mov_b32_e32 v2, 0x22000
	ds_read_b32 v4, v2
	s_lshl_b32 s1, s87, 8
	s_add_i32 s1, s1, 0x2b5d02c
	v_mov_b32_e32 v2, s1
	global_atomic_add v6, v2, v3, s[88:89] sc0
	s_waitcnt vmcnt(0) lgkmcnt(0)
	v_add_u32_e32 v6, 1, v6
	v_cmp_eq_u32_e32 vcc, v6, v4
	s_cbranch_vccz .Lp15_notlast
	buffer_wbl2 sc1
	s_waitcnt vmcnt(0)
	v_mov_b32_e32 v2, 0x2b5d030
	global_atomic_add v2, v3, s[88:89]
.Lp15_notlast:
	s_lshr_b32 s1, s2, 3
	s_and_b32 s1, s1, 7
	s_add_i32 s1, s0, s1
	s_lshl_b32 s1, s1, 8
	s_add_i32 s1, s1, 0x2b5d028
	v_mov_b32_e32 v2, s1
	s_mov_b32 s1, 0x100000

.Lp15_pdone:
	buffer_inv sc1
	s_waitcnt vmcnt(0)
.LBB0_1833:
	s_or_b64 exec, exec, s[8:9]
	v_readlane_b32 s0, v254, 5
	v_readlane_b32 s1, v254, 6
	s_waitcnt lgkmcnt(0)
	v_mov_b32_e32 v2, v0
	s_and_b64 vcc, exec, s[0:1]
	s_barrier
	s_cbranch_vccnz .LBB0_1835
	s_ashr_i32 s0, s2, 31
	s_lshr_b32 s0, s0, 29
	s_add_i32 s0, s2, s0
	s_ashr_i32 s1, s0, 3
	s_and_b32 s0, s0, -8
	s_sub_i32 s0, s2, s0
	s_lshr_b32 s2, s0, 31
	s_or_b32 s2, s2, 32
	s_mul_i32 s0, s2, s0
	s_add_i32 s0, s0, s1
	s_ashr_i32 s1, s0, 31
	s_lshr_b32 s1, s1, 27
	s_add_i32 s1, s0, s1
	s_ashr_i32 s2, s1, 5
	s_lshl_b32 s2, s2, 3
	s_sub_i32 s3, 64, s2
	s_min_u32 s3, s3, 8
	s_andn2_b32 s1, s1, 31
	s_sub_i32 s4, s0, s1
	v_cvt_f32_ubyte0_e32 v3, s3
	v_cvt_f32_i32_e32 v2, s4
	v_rcp_iflag_f32_e32 v4, v3
	s_ashr_i32 s0, s4, 30
	s_or_b32 s5, s0, 1
	v_mul_f32_e32 v4, v2, v4
	v_trunc_f32_e32 v4, v4
	v_fma_f32 v2, -v4, v3, v2
	v_cvt_i32_f32_e32 v4, v4
	v_cmp_ge_f32_e64 s[0:1], |v2|, v3
	s_and_b64 s[0:1], s[0:1], exec
	s_cselect_b32 s0, s5, 0
	v_readfirstlane_b32 s1, v4
	s_add_i32 s0, s1, s0
	s_mul_i32 s1, s0, s3
	s_sub_i32 s1, s4, s1
	s_sext_i32_i8 s1, s1
	s_add_i32 s14, s2, s1
	s_sext_i32_i8 s16, s0

.LBB0_1842:
	s_cmp_lg_u32 s45, 8
	s_cbranch_scc1 .Lp15w_skip
	s_cmp_eq_u64 s[92:93], 0
	s_cbranch_scc1 .Lp15w_skip
	v_mov_b32_e32 v255, 0x22004
	ds_read_b32 v255, v255
	s_mov_b32 s100, 0x100000
	s_waitcnt lgkmcnt(0)
	v_readfirstlane_b32 s98, v255
.Lp15w_poll:
	v_mov_b32_e32 v255, 0x2b5d030
	global_load_dword v255, v255, s[88:89] sc1
	s_waitcnt vmcnt(0)
	v_readfirstlane_b32 s99, v255
	s_cmp_ge_u32 s99, s98
	s_cbranch_scc1 .Lp15w_skip
	s_sleep 1
	s_sub_u32 s100, s100, 1
	s_cmp_lg_u32 s100, 0
	s_cbranch_scc1 .Lp15w_poll

	.amdhsa_kernel _Z6mk_fwdILj262143EEv6Params
		.amdhsa_group_segment_fixed_size 0
		.amdhsa_private_segment_fixed_size 0
		.amdhsa_kernarg_size 496
		.amdhsa_user_sgpr_count 2
		.amdhsa_user_sgpr_dispatch_ptr 0
		.amdhsa_user_sgpr_queue_ptr 0
		.amdhsa_user_sgpr_kernarg_segment_ptr 1
		.amdhsa_user_sgpr_dispatch_id 0
		.amdhsa_user_sgpr_kernarg_preload_length 0
		.amdhsa_user_sgpr_kernarg_preload_offset 0
		.amdhsa_user_sgpr_private_segment_size 0
		.amdhsa_uses_dynamic_stack 0
		.amdhsa_enable_private_segment 0
		.amdhsa_system_sgpr_workgroup_id_x 1
		.amdhsa_system_sgpr_workgroup_id_y 0
		.amdhsa_system_sgpr_workgroup_id_z 0
		.amdhsa_system_sgpr_workgroup_info 0
		.amdhsa_system_vgpr_workitem_id 0
		.amdhsa_next_free_vgpr 256
		.amdhsa_next_free_sgpr 102
		.amdhsa_accum_offset 256
		.amdhsa_reserve_vcc 1
		.amdhsa_float_round_mode_32 0
		.amdhsa_float_round_mode_16_64 0
		.amdhsa_float_denorm_mode_32 3
		.amdhsa_float_denorm_mode_16_64 3
		.amdhsa_dx10_clamp 1
		.amdhsa_ieee_mode 1
		.amdhsa_fp16_overflow 0
		.amdhsa_tg_split 0
		.amdhsa_exception_fp_ieee_invalid_op 0
		.amdhsa_exception_fp_denorm_src 0
		.amdhsa_exception_fp_ieee_div_zero 0
		.amdhsa_exception_fp_ieee_overflow 0
		.amdhsa_exception_fp_ieee_underflow 0
		.amdhsa_exception_fp_ieee_inexact 0
		.amdhsa_exception_int_div_zero 0
	.end_amdhsa_kernel

amdhsa.kernels:
  - .agpr_count:     0
    .args:
      - .offset:         0
        .size:           240
        .value_kind:     by_value
      - .offset:         240
        .size:           4
        .value_kind:     hidden_block_count_x
      - .offset:         244
        .size:           4
        .value_kind:     hidden_block_count_y
      - .offset:         248
        .size:           4
        .value_kind:     hidden_block_count_z
      - .offset:         252
        .size:           2
        .value_kind:     hidden_group_size_x
      - .offset:         254
        .size:           2
        .value_kind:     hidden_group_size_y
      - .offset:         256
        .size:           2
        .value_kind:     hidden_group_size_z
      - .offset:         258
        .size:           2
        .value_kind:     hidden_remainder_x
      - .offset:         260
        .size:           2
        .value_kind:     hidden_remainder_y
      - .offset:         262
        .size:           2
        .value_kind:     hidden_remainder_z
      - .offset:         280
        .size:           8
        .value_kind:     hidden_global_offset_x
      - .offset:         288
        .size:           8
        .value_kind:     hidden_global_offset_y
      - .offset:         296
        .size:           8
        .value_kind:     hidden_global_offset_z
      - .offset:         304
        .size:           2
        .value_kind:     hidden_grid_dims
      - .offset:         360
        .size:           4
        .value_kind:     hidden_dynamic_lds_size
    .group_segment_fixed_size: 0
    .kernarg_segment_align: 8
    .kernarg_segment_size: 496
    .language:       OpenCL C
    .language_version:
      - 2
      - 0
    .max_flat_workgroup_size: 512
    .name:           _Z6mk_fwdILj262143EEv6Params
    .private_segment_fixed_size: 0
    .sgpr_count:     108
    .sgpr_spill_count: 30
    .symbol:         _Z6mk_fwdILj262143EEv6Params.kd
    .uniform_work_group_size: 1
    .uses_dynamic_stack: false
    .vgpr_count:     256
    .vgpr_spill_count: 0
    .wavefront_size: 64
